# v10 + P0 RMSNorm bf16 path: next row's 8 loads prefetched into spare registers while the current row is reduced; redundant gain-load vmcnt waits removed
# baseline (speedup 1.0000x reference)
.LBB0_72:
	s_or_b64 exec, exec, s[8:9]
	s_waitcnt lgkmcnt(0)
	s_cmpk_gt_i32 s4, 0x7fff
	s_waitcnt lgkmcnt(0)
	s_barrier
	s_cbranch_scc1 .LBB0_83
	v_lshlrev_b32_e32 v70, 4, v68
	v_mov_b32_e32 v71, v35
	v_lshl_add_u64 v[2:3], s[6:7], 0, v[70:71]
	v_add_co_u32_e32 v2, vcc, 0x1000, v2
	global_load_dwordx4 v[36:39], v70, s[6:7]
	global_load_dwordx4 v[40:43], v70, s[6:7] offset:1024
	global_load_dwordx4 v[44:47], v70, s[6:7] offset:2048
	global_load_dwordx4 v[48:51], v70, s[6:7] offset:3072
	v_addc_co_u32_e32 v3, vcc, 0, v3, vcc
	global_load_dwordx4 v[52:55], v[2:3], off
	global_load_dwordx4 v[56:59], v[2:3], off offset:1024
	global_load_dwordx4 v[60:63], v[2:3], off offset:2048
	global_load_dwordx4 v[64:67], v[2:3], off offset:3072
	v_and_b32_e32 v1, 64, v217
	v_add_u32_e32 v2, 64, v1
	v_xor_b32_e32 v1, 1, v217
	v_cmp_lt_i32_e32 vcc, v1, v2
	v_xor_b32_e32 v3, 2, v217
	v_readlane_b32 s56, v252, 19
	v_cndmask_b32_e32 v1, v217, v1, vcc
	v_cmp_lt_i32_e32 vcc, v3, v2
	s_cmp_eq_u32 s72, 0
	v_readlane_b32 s57, v252, 20
	v_cndmask_b32_e32 v3, v217, v3, vcc
	v_lshlrev_b32_e32 v69, 2, v3
	v_xor_b32_e32 v3, 4, v217
	v_cmp_lt_i32_e32 vcc, v3, v2
	s_mul_i32 s92, s72, 5
	v_readlane_b32 s62, v252, 25
	v_cndmask_b32_e32 v3, v217, v3, vcc
	v_lshlrev_b32_e32 v94, 2, v3
	v_xor_b32_e32 v3, 8, v217
	v_cmp_lt_i32_e32 vcc, v3, v2
	s_cselect_b32 s9, s57, 0
	s_cselect_b32 s8, s56, 0
	v_cndmask_b32_e32 v3, v217, v3, vcc
	v_lshlrev_b32_e32 v95, 2, v3
	v_xor_b32_e32 v3, 16, v217
	s_lshl_b64 s[6:7], s[92:93], 2
	v_cmp_lt_i32_e32 vcc, v3, v2
	v_readlane_b32 s63, v252, 26
	s_add_u32 s10, s62, s6
	v_cndmask_b32_e32 v3, v217, v3, vcc
	s_addc_u32 s11, s63, s7
	v_lshlrev_b32_e32 v96, 2, v3
	v_xor_b32_e32 v3, 32, v217
	v_lshlrev_b32_e32 v34, 2, v68
	s_cmp_lg_u64 s[8:9], 0
	v_cmp_lt_i32_e32 vcc, v3, v2
	v_lshl_add_u64 v[74:75], s[8:9], 0, v[70:71]
	v_readlane_b32 s8, v254, 38
	v_cndmask_b32_e32 v2, v217, v3, vcc
	v_lshl_add_u64 v[72:73], s[10:11], 0, v[34:35]
	v_lshlrev_b32_e32 v34, 3, v68
	v_readlane_b32 s9, v254, 39
	s_cselect_b64 s[6:7], -1, 0
	v_lshlrev_b32_e32 v1, 2, v1
	v_lshlrev_b32_e32 v97, 2, v2
	v_cmp_eq_u32_e64 s[38:39], 0, v68
	v_cmp_gt_u32_e64 s[40:41], 5, v68
	v_cmp_eq_u32_e64 s[42:43], 1, v68
	v_cmp_eq_u32_e64 s[44:45], 2, v68
	v_cmp_eq_u32_e64 s[46:47], 3, v68
	v_cmp_eq_u32_e64 s[48:49], 4, v68
	v_lshl_add_u64 v[76:77], s[8:9], 0, v[34:35]
	v_readlane_b32 s58, v252, 21
	v_readlane_b32 s59, v252, 22
	v_readlane_b32 s60, v252, 23
	v_readlane_b32 s61, v252, 24
	v_readlane_b32 s64, v252, 27
	v_readlane_b32 s65, v252, 28
	v_readlane_b32 s66, v252, 29
	v_readlane_b32 s67, v252, 30
	v_readlane_b32 s68, v252, 31
	v_readlane_b32 s69, v252, 32
	v_readlane_b32 s70, v252, 33
	v_readlane_b32 s71, v252, 34
	s_and_b64 vcc, exec, s[6:7]
	s_cbranch_vccnz .Lrn_pf0_skip
	s_ashr_i32 s5, s4, 31
	s_lshl_b64 s[8:9], s[4:5], 12
	v_lshl_add_u64 v[116:117], v[76:77], 0, s[8:9]
	global_load_dwordx2 v[100:101], v[116:117], off
	global_load_dwordx2 v[102:103], v[116:117], off offset:512
	global_load_dwordx2 v[104:105], v[116:117], off offset:1024
	global_load_dwordx2 v[106:107], v[116:117], off offset:1536
	global_load_dwordx2 v[108:109], v[116:117], off offset:2048
	global_load_dwordx2 v[110:111], v[116:117], off offset:2560
	global_load_dwordx2 v[112:113], v[116:117], off offset:3072
	global_load_dwordx2 v[114:115], v[116:117], off offset:3584
.Lrn_pf0_skip:
	s_branch .LBB0_75
.LBB0_74:
	s_or_b64 exec, exec, s[8:9]
	s_add_i32 s4, s4, s78
	s_cmp_lt_i32 s4, 0x8000
	s_cbranch_scc0 .LBB0_83

.LBB0_77:
	s_waitcnt lgkmcnt(0)
	s_waitcnt vmcnt(0)
	v_lshlrev_b32_e32 v2, 16, v100
	v_and_b32_e32 v3, 0xffff0000, v100
	v_lshlrev_b32_e32 v4, 16, v101
	v_and_b32_e32 v5, 0xffff0000, v101
	v_lshlrev_b32_e32 v6, 16, v102
	v_and_b32_e32 v7, 0xffff0000, v102
	v_lshlrev_b32_e32 v8, 16, v103
	v_and_b32_e32 v9, 0xffff0000, v103
	v_lshlrev_b32_e32 v10, 16, v104
	v_and_b32_e32 v11, 0xffff0000, v104
	v_lshlrev_b32_e32 v12, 16, v105
	v_and_b32_e32 v13, 0xffff0000, v105
	v_lshlrev_b32_e32 v14, 16, v106
	v_and_b32_e32 v15, 0xffff0000, v106
	v_lshlrev_b32_e32 v16, 16, v107
	v_and_b32_e32 v17, 0xffff0000, v107
	v_lshlrev_b32_e32 v18, 16, v108
	v_and_b32_e32 v19, 0xffff0000, v108
	v_lshlrev_b32_e32 v20, 16, v109
	v_and_b32_e32 v21, 0xffff0000, v109
	v_lshlrev_b32_e32 v22, 16, v110
	v_and_b32_e32 v23, 0xffff0000, v110
	v_lshlrev_b32_e32 v24, 16, v111
	v_and_b32_e32 v25, 0xffff0000, v111
	v_lshlrev_b32_e32 v26, 16, v112
	v_and_b32_e32 v27, 0xffff0000, v112
	v_lshlrev_b32_e32 v28, 16, v113
	v_and_b32_e32 v29, 0xffff0000, v113
	v_lshlrev_b32_e32 v30, 16, v114
	v_and_b32_e32 v31, 0xffff0000, v114
	v_lshlrev_b32_e32 v32, 16, v115
	v_and_b32_e32 v33, 0xffff0000, v115
	s_add_i32 s8, s4, s78
	s_cmp_lt_i32 s8, 0x8000
	s_cbranch_scc0 .Lrn_pf_skip
	s_ashr_i32 s9, s8, 31
	s_lshl_b64 s[8:9], s[8:9], 12
	v_lshl_add_u64 v[116:117], v[76:77], 0, s[8:9]
	global_load_dwordx2 v[100:101], v[116:117], off
	global_load_dwordx2 v[102:103], v[116:117], off offset:512
	global_load_dwordx2 v[104:105], v[116:117], off offset:1024
	global_load_dwordx2 v[106:107], v[116:117], off offset:1536
	global_load_dwordx2 v[108:109], v[116:117], off offset:2048
	global_load_dwordx2 v[110:111], v[116:117], off offset:2560
	global_load_dwordx2 v[112:113], v[116:117], off offset:3072
	global_load_dwordx2 v[114:115], v[116:117], off offset:3584
.Lrn_pf_skip:
.LBB0_78:
	s_waitcnt lgkmcnt(0)
	v_pk_mul_f32 v[86:87], v[4:5], v[4:5]
	v_pk_mul_f32 v[88:89], v[8:9], v[8:9]
	v_pk_mul_f32 v[90:91], v[6:7], v[6:7]
	v_pk_mul_f32 v[92:93], v[2:3], v[2:3]
	v_pk_mul_f32 v[82:83], v[12:13], v[12:13]
	v_pk_mul_f32 v[84:85], v[10:11], v[10:11]
	v_mov_b32_e32 v98, v92
	v_mov_b32_e32 v99, v90
	v_mov_b32_e32 v90, v93
	v_mov_b32_e32 v92, v86
	v_mov_b32_e32 v93, v88
	v_mov_b32_e32 v88, v87
	v_pk_add_f32 v[90:91], v[98:99], v[90:91]
	v_pk_add_f32 v[86:87], v[92:93], v[88:89]
	v_pk_mov_b32 v[88:89], v[84:85], v[82:83] op_sel:[1,0]
	v_mov_b32_e32 v85, v83
	v_mul_f32_e32 v34, v14, v14
	v_pk_add_f32 v[86:87], v[90:91], v[86:87]
	v_pk_add_f32 v[82:83], v[88:89], v[84:85]
	v_pk_fma_f32 v[84:85], v[14:15], v[14:15], v[34:35] op_sel_hi:[1,1,0]
	v_mul_f32_e32 v34, v16, v16
	v_pk_add_f32 v[86:87], v[86:87], v[86:87] op_sel_hi:[0,1]
	v_pk_add_f32 v[82:83], v[82:83], v[82:83] op_sel_hi:[0,1]
	v_pk_fma_f32 v[88:89], v[16:17], v[16:17], v[34:35] op_sel_hi:[1,1,0]
	v_mul_f32_e32 v84, v18, v18
	v_mul_f32_e32 v88, v19, v19
	v_mul_f32_e32 v82, v20, v20
	v_mul_f32_e32 v86, v21, v21
	v_pk_mul_f32 v[78:79], v[24:25], v[24:25]
	v_pk_mul_f32 v[80:81], v[22:23], v[22:23]
	v_pk_add_f32 v[84:85], v[84:85], v[88:89]
	v_pk_add_f32 v[82:83], v[82:83], v[86:87]
	v_mul_f32_e32 v34, v26, v26
	v_pk_add_f32 v[82:83], v[84:85], v[82:83]
	v_pk_mov_b32 v[84:85], v[80:81], v[78:79] op_sel:[1,0]
	v_mov_b32_e32 v81, v79
	v_pk_add_f32 v[78:79], v[84:85], v[80:81]
	v_pk_fma_f32 v[80:81], v[26:27], v[26:27], v[34:35] op_sel_hi:[1,1,0]
	v_mul_f32_e32 v34, v28, v28
	v_pk_add_f32 v[82:83], v[82:83], v[82:83] op_sel_hi:[0,1]
	v_pk_add_f32 v[78:79], v[78:79], v[78:79] op_sel_hi:[0,1]
	v_pk_fma_f32 v[84:85], v[28:29], v[28:29], v[34:35] op_sel_hi:[1,1,0]
	v_mul_f32_e32 v80, v30, v30
	v_mul_f32_e32 v84, v31, v31
	v_mul_f32_e32 v78, v32, v32
	v_mul_f32_e32 v82, v33, v33
	v_pk_add_f32 v[80:81], v[80:81], v[84:85]
	v_pk_add_f32 v[78:79], v[78:79], v[82:83]
	s_mov_b32 s8, 0xf800000
	v_pk_add_f32 v[78:79], v[80:81], v[78:79]
	s_nop 0
	v_add_f32_e32 v34, v78, v79
	ds_bpermute_b32 v71, v1, v34
	s_waitcnt lgkmcnt(0)
	v_add_f32_e32 v34, v34, v71
	ds_bpermute_b32 v71, v69, v34
	s_waitcnt lgkmcnt(0)
	v_add_f32_e32 v34, v34, v71
	ds_bpermute_b32 v71, v94, v34
	s_waitcnt lgkmcnt(0)
	v_add_f32_e32 v34, v34, v71
	ds_bpermute_b32 v71, v95, v34
	s_waitcnt lgkmcnt(0)
	v_add_f32_e32 v34, v34, v71
	ds_bpermute_b32 v71, v96, v34
	s_waitcnt lgkmcnt(0)
	v_add_f32_e32 v34, v34, v71
	ds_bpermute_b32 v71, v97, v34
	s_waitcnt lgkmcnt(0)
	v_add_f32_e32 v34, v34, v71
	v_fmamk_f32 v34, v34, 0x3a000000, v214
	v_mul_f32_e32 v71, 0x4f800000, v34
	v_cmp_gt_f32_e32 vcc, s8, v34
	s_nop 1
	v_cndmask_b32_e32 v34, v34, v71, vcc
	v_sqrt_f32_e32 v71, v34
	s_nop 0
	v_add_u32_e32 v78, -1, v71
	v_fma_f32 v79, -v78, v71, v34
	v_cmp_ge_f32_e64 s[50:51], 0, v79
	v_add_u32_e32 v79, 1, v71
	s_nop 0
	v_cndmask_b32_e64 v78, v71, v78, s[50:51]
	v_fma_f32 v71, -v79, v71, v34
	v_cmp_lt_f32_e64 s[50:51], 0, v71
	s_nop 1
	v_cndmask_b32_e64 v71, v78, v79, s[50:51]
	v_mul_f32_e32 v78, 0x37800000, v71
	v_cndmask_b32_e32 v71, v71, v78, vcc
	v_cmp_class_f32_e32 vcc, v34, v215
	s_nop 1
	v_cndmask_b32_e32 v34, v71, v34, vcc
	v_div_scale_f32 v71, s[8:9], v34, v34, 1.0
	v_rcp_f32_e32 v78, v71
	s_nop 0
	v_fma_f32 v79, -v71, v78, 1.0
	v_fmac_f32_e32 v78, v79, v78
	v_div_scale_f32 v79, vcc, 1.0, v34, 1.0
	v_mul_f32_e32 v80, v79, v78
	v_fma_f32 v81, -v71, v80, v79
	v_fmac_f32_e32 v80, v81, v78
	v_fma_f32 v71, -v71, v80, v79
	v_div_fmas_f32 v71, v71, v78, v80
	v_div_fixup_f32 v34, v71, v34, 1.0
	s_and_saveexec_b64 s[8:9], s[38:39]
	s_cbranch_execz .LBB0_80
	s_lshl_b64 s[10:11], s[4:5], 2
	s_add_u32 s10, s76, s10
	s_addc_u32 s11, s77, s11
	global_store_dword v35, v34, s[10:11]
.LBB0_80:
	s_or_b64 exec, exec, s[8:9]
	v_pk_mul_f32 v[2:3], v[2:3], v[34:35] op_sel_hi:[1,0]
	v_pk_mul_f32 v[4:5], v[4:5], v[34:35] op_sel_hi:[1,0]
	v_pk_mul_f32 v[92:93], v[36:37], v[2:3]
	v_pk_mul_f32 v[2:3], v[6:7], v[34:35] op_sel_hi:[1,0]
	v_pk_mul_f32 v[88:89], v[38:39], v[4:5]
	v_pk_mul_f32 v[4:5], v[8:9], v[34:35] op_sel_hi:[1,0]
	v_pk_mul_f32 v[90:91], v[40:41], v[2:3]
	v_pk_mul_f32 v[2:3], v[10:11], v[34:35] op_sel_hi:[1,0]
	v_pk_mul_f32 v[86:87], v[42:43], v[4:5]
	v_pk_mul_f32 v[4:5], v[12:13], v[34:35] op_sel_hi:[1,0]
	v_pk_mul_f32 v[84:85], v[44:45], v[2:3]
	v_pk_mul_f32 v[2:3], v[14:15], v[34:35] op_sel_hi:[1,0]
	v_pk_mul_f32 v[80:81], v[46:47], v[4:5]
	v_pk_mul_f32 v[4:5], v[16:17], v[34:35] op_sel_hi:[1,0]
	v_pk_mul_f32 v[82:83], v[48:49], v[2:3]
	v_pk_mul_f32 v[2:3], v[18:19], v[34:35] op_sel_hi:[1,0]
	v_add_u32_e32 v18, 0, v70
	v_pk_mul_f32 v[78:79], v[50:51], v[4:5]
	v_pk_mul_f32 v[4:5], v[20:21], v[34:35] op_sel_hi:[1,0]
	v_pk_mul_f32 v[16:17], v[52:53], v[2:3]
	v_pk_mul_f32 v[2:3], v[22:23], v[34:35] op_sel_hi:[1,0]
	ds_read_b128 v[20:23], v18
	v_pk_mul_f32 v[12:13], v[54:55], v[4:5]
	v_pk_mul_f32 v[4:5], v[24:25], v[34:35] op_sel_hi:[1,0]
	v_pk_mul_f32 v[14:15], v[56:57], v[2:3]
	v_pk_mul_f32 v[8:9], v[58:59], v[4:5]
	v_pk_mul_f32 v[4:5], v[26:27], v[34:35] op_sel_hi:[1,0]
	ds_read_b128 v[24:27], v18 offset:1024
	s_waitcnt lgkmcnt(1)
	v_mul_f32_e32 v19, v93, v21
	v_fmac_f32_e32 v19, v92, v20
	v_mul_f32_e32 v20, v89, v23
	v_fmac_f32_e32 v20, v88, v22
	s_waitcnt lgkmcnt(0)
	v_mul_f32_e32 v25, v91, v25
	v_add_f32_e32 v19, v19, v20
	v_fmac_f32_e32 v25, v90, v24
	v_mul_f32_e32 v24, v87, v27
	ds_read_b128 v[20:23], v18 offset:2048
	v_fmac_f32_e32 v24, v86, v26
	v_add_f32_e32 v19, 0, v19
	v_add_f32_e32 v24, v25, v24
	v_add_f32_e32 v19, v19, v24
	ds_read_b128 v[24:27], v18 offset:3072
	s_waitcnt lgkmcnt(1)
	v_mul_f32_e32 v21, v85, v21
	v_fmac_f32_e32 v21, v84, v20
	v_mul_f32_e32 v20, v81, v23
	v_fmac_f32_e32 v20, v80, v22
	v_add_f32_e32 v20, v21, v20
	s_waitcnt lgkmcnt(0)
	v_mul_f32_e32 v25, v83, v25
	v_add_f32_e32 v19, v19, v20
	v_fmac_f32_e32 v25, v82, v24
	v_mul_f32_e32 v24, v79, v27
	ds_read_b128 v[20:23], v18 offset:4096
	v_fmac_f32_e32 v24, v78, v26
	v_add_f32_e32 v24, v25, v24
	v_add_f32_e32 v19, v19, v24
	ds_read_b128 v[24:27], v18 offset:5120
	s_waitcnt lgkmcnt(1)
	v_mul_f32_e32 v21, v17, v21
	v_fmac_f32_e32 v21, v16, v20
	v_mul_f32_e32 v20, v13, v23
	v_fmac_f32_e32 v20, v12, v22
	v_add_f32_e32 v20, v21, v20
	s_waitcnt lgkmcnt(0)
	v_mul_f32_e32 v25, v15, v25
	v_add_f32_e32 v19, v19, v20
	v_fmac_f32_e32 v25, v14, v24
	v_mul_f32_e32 v24, v9, v27
	ds_read_b128 v[20:23], v18 offset:6144
	v_fmac_f32_e32 v24, v8, v26
	v_add_f32_e32 v24, v25, v24
	v_add_f32_e32 v19, v19, v24
	ds_read_b128 v[24:27], v18 offset:7168
	v_pk_mul_f32 v[2:3], v[28:29], v[34:35] op_sel_hi:[1,0]
	v_pk_mul_f32 v[4:5], v[60:61], v[4:5]
	v_pk_mul_f32 v[2:3], v[62:63], v[2:3]
	s_waitcnt lgkmcnt(1)
	v_mul_f32_e32 v21, v5, v21
	v_pk_mul_f32 v[10:11], v[30:31], v[34:35] op_sel_hi:[1,0]
	v_fmac_f32_e32 v21, v4, v20
	v_mul_f32_e32 v20, v3, v23
	v_pk_mul_f32 v[6:7], v[32:33], v[34:35] op_sel_hi:[1,0]
	v_pk_mul_f32 v[10:11], v[64:65], v[10:11]
	v_fmac_f32_e32 v20, v2, v22
	v_pk_mul_f32 v[6:7], v[66:67], v[6:7]
	v_add_f32_e32 v20, v21, v20
	s_waitcnt lgkmcnt(0)
	v_mul_f32_e32 v25, v11, v25
	v_add_f32_e32 v19, v19, v20
	v_fmac_f32_e32 v25, v10, v24
	v_mul_f32_e32 v24, v7, v27
	ds_read_b128 v[20:23], v18 offset:8192
	v_fmac_f32_e32 v24, v6, v26
	v_add_f32_e32 v24, v25, v24
	v_add_f32_e32 v19, v19, v24
	ds_read_b128 v[24:27], v18 offset:9216
	s_waitcnt lgkmcnt(1)
	v_mul_f32_e32 v21, v93, v21
	v_fmac_f32_e32 v21, v92, v20
	v_mul_f32_e32 v20, v89, v23
	v_fmac_f32_e32 v20, v88, v22
	v_add_f32_e32 v20, v21, v20
	s_waitcnt lgkmcnt(0)
	v_mul_f32_e32 v25, v91, v25
	v_add_f32_e32 v29, 0, v20
	v_fmac_f32_e32 v25, v90, v24
	v_mul_f32_e32 v24, v87, v27
	ds_read_b128 v[20:23], v18 offset:10240
	v_fmac_f32_e32 v24, v86, v26
	v_add_f32_e32 v24, v25, v24
	v_add_f32_e32 v29, v29, v24
	ds_read_b128 v[24:27], v18 offset:11264
	s_waitcnt lgkmcnt(1)
	v_mul_f32_e32 v21, v85, v21
	v_fmac_f32_e32 v21, v84, v20
	v_mul_f32_e32 v20, v81, v23
	v_fmac_f32_e32 v20, v80, v22
	v_add_f32_e32 v20, v21, v20
	s_waitcnt lgkmcnt(0)
	v_mul_f32_e32 v25, v83, v25
	v_add_f32_e32 v29, v29, v20
	v_fmac_f32_e32 v25, v82, v24
	v_mul_f32_e32 v24, v79, v27
	ds_read_b128 v[20:23], v18 offset:12288
	v_fmac_f32_e32 v24, v78, v26
	v_add_f32_e32 v24, v25, v24
	v_add_f32_e32 v29, v29, v24
	ds_read_b128 v[24:27], v18 offset:13312
	s_waitcnt lgkmcnt(1)
	v_mul_f32_e32 v21, v17, v21
	v_fmac_f32_e32 v21, v16, v20
	v_mul_f32_e32 v20, v13, v23
	v_fmac_f32_e32 v20, v12, v22
	v_add_f32_e32 v20, v21, v20
	s_waitcnt lgkmcnt(0)
	v_mul_f32_e32 v25, v15, v25
	v_add_f32_e32 v29, v29, v20
	v_fmac_f32_e32 v25, v14, v24
	v_mul_f32_e32 v24, v9, v27
	ds_read_b128 v[20:23], v18 offset:14336
	v_fmac_f32_e32 v24, v8, v26
	v_add_f32_e32 v24, v25, v24
	v_add_f32_e32 v29, v29, v24
	ds_read_b128 v[24:27], v18 offset:15360
	s_waitcnt lgkmcnt(1)
	v_mul_f32_e32 v21, v5, v21
	v_fmac_f32_e32 v21, v4, v20
	v_mul_f32_e32 v20, v3, v23
	v_fmac_f32_e32 v20, v2, v22
	v_add_f32_e32 v20, v21, v20
	s_waitcnt lgkmcnt(0)
	v_mul_f32_e32 v21, v11, v25
	v_mul_f32_e32 v22, v7, v27
	v_fmac_f32_e32 v21, v10, v24
	v_fmac_f32_e32 v22, v6, v26
	v_add_f32_e32 v20, v29, v20
	v_add_f32_e32 v21, v21, v22
	v_add_f32_e32 v20, v20, v21
	ds_bpermute_b32 v21, v1, v20
	ds_bpermute_b32 v28, v1, v19
	ds_read_b128 v[24:27], v18 offset:16384
	s_waitcnt lgkmcnt(2)
	v_add_f32_e32 v20, v20, v21
	ds_bpermute_b32 v21, v69, v20
	s_waitcnt lgkmcnt(2)
	v_add_f32_e32 v19, v19, v28
	ds_read_b128 v[28:31], v18 offset:17408
	ds_bpermute_b32 v22, v69, v19
	s_waitcnt lgkmcnt(2)
	v_add_f32_e32 v20, v20, v21
	ds_bpermute_b32 v21, v94, v20
	s_waitcnt lgkmcnt(2)
	v_mul_f32_e32 v29, v91, v29
	v_fmac_f32_e32 v29, v90, v28
	v_mul_f32_e32 v28, v87, v31
	v_fmac_f32_e32 v28, v86, v30
	s_waitcnt lgkmcnt(0)
	v_add_f32_e32 v20, v20, v21
	ds_bpermute_b32 v21, v95, v20
	v_add_f32_e32 v28, v29, v28
	v_add_f32_e32 v19, v19, v22
	ds_bpermute_b32 v22, v94, v19
	s_waitcnt lgkmcnt(1)
	v_add_f32_e32 v21, v20, v21
	ds_bpermute_b32 v23, v96, v21
	s_waitcnt lgkmcnt(1)
	v_add_f32_e32 v19, v19, v22
	ds_bpermute_b32 v22, v95, v19
	s_waitcnt lgkmcnt(1)
	v_add_f32_e32 v21, v21, v23
	v_mul_f32_e32 v23, v93, v25
	v_fmac_f32_e32 v23, v92, v24
	v_mul_f32_e32 v24, v89, v27
	v_fmac_f32_e32 v24, v88, v26
	v_add_f32_e32 v23, v23, v24
	ds_read_b128 v[24:27], v18 offset:18432
	v_add_f32_e32 v23, 0, v23
	v_add_f32_e32 v23, v23, v28
	ds_read_b128 v[28:31], v18 offset:19456
	s_waitcnt lgkmcnt(2)
	v_add_f32_e32 v19, v19, v22
	s_waitcnt lgkmcnt(1)
	v_mul_f32_e32 v25, v85, v25
	v_fmac_f32_e32 v25, v84, v24
	v_mul_f32_e32 v24, v81, v27
	v_fmac_f32_e32 v24, v80, v26
	s_waitcnt lgkmcnt(0)
	v_mul_f32_e32 v29, v83, v29
	v_add_f32_e32 v24, v25, v24
	v_fmac_f32_e32 v29, v82, v28
	v_mul_f32_e32 v28, v79, v31
	v_add_f32_e32 v23, v23, v24
	ds_read_b128 v[24:27], v18 offset:20480
	v_fmac_f32_e32 v28, v78, v30
	v_add_f32_e32 v28, v29, v28
	v_add_f32_e32 v23, v23, v28
	ds_read_b128 v[28:31], v18 offset:21504
	s_waitcnt lgkmcnt(1)
	v_mul_f32_e32 v25, v17, v25
	v_fmac_f32_e32 v25, v16, v24
	v_mul_f32_e32 v24, v13, v27
	v_fmac_f32_e32 v24, v12, v26
	s_waitcnt lgkmcnt(0)
	v_mul_f32_e32 v29, v15, v29
	v_add_f32_e32 v24, v25, v24
	v_fmac_f32_e32 v29, v14, v28
	v_mul_f32_e32 v28, v9, v31
	v_add_f32_e32 v23, v23, v24
	ds_read_b128 v[24:27], v18 offset:22528
	v_fmac_f32_e32 v28, v8, v30
	v_add_f32_e32 v28, v29, v28
	v_add_f32_e32 v23, v23, v28
	ds_read_b128 v[28:31], v18 offset:23552
	s_waitcnt lgkmcnt(1)
	v_mul_f32_e32 v25, v5, v25
	v_fmac_f32_e32 v25, v4, v24
	v_mul_f32_e32 v24, v3, v27
	v_fmac_f32_e32 v24, v2, v26
	s_waitcnt lgkmcnt(0)
	v_mul_f32_e32 v29, v11, v29
	v_add_f32_e32 v24, v25, v24
	v_fmac_f32_e32 v29, v10, v28
	v_mul_f32_e32 v28, v7, v31
	v_add_f32_e32 v23, v23, v24
	v_fmac_f32_e32 v28, v6, v30
	ds_read_b128 v[24:27], v18 offset:24576
	v_add_f32_e32 v28, v29, v28
	v_add_f32_e32 v23, v23, v28
	ds_read_b128 v[28:31], v18 offset:25600
	ds_bpermute_b32 v32, v1, v23
	s_waitcnt lgkmcnt(2)
	v_mul_f32_e32 v25, v93, v25
	v_fmac_f32_e32 v25, v92, v24
	v_mul_f32_e32 v24, v89, v27
	v_fmac_f32_e32 v24, v88, v26
	s_waitcnt lgkmcnt(1)
	v_mul_f32_e32 v29, v91, v29
	v_add_f32_e32 v24, v25, v24
	v_fmac_f32_e32 v29, v90, v28
	v_mul_f32_e32 v28, v87, v31
	v_add_f32_e32 v33, 0, v24
	ds_read_b128 v[24:27], v18 offset:26624
	v_fmac_f32_e32 v28, v86, v30
	v_add_f32_e32 v28, v29, v28
	v_add_f32_e32 v33, v33, v28
	ds_read_b128 v[28:31], v18 offset:27648
	s_waitcnt lgkmcnt(1)
	v_mul_f32_e32 v25, v85, v25
	v_fmac_f32_e32 v25, v84, v24
	v_mul_f32_e32 v24, v81, v27
	v_fmac_f32_e32 v24, v80, v26
	s_waitcnt lgkmcnt(0)
	v_mul_f32_e32 v29, v83, v29
	v_add_f32_e32 v24, v25, v24
	v_fmac_f32_e32 v29, v82, v28
	v_mul_f32_e32 v28, v79, v31
	v_add_f32_e32 v33, v33, v24
	ds_read_b128 v[24:27], v18 offset:28672
	v_fmac_f32_e32 v28, v78, v30
	v_add_f32_e32 v28, v29, v28
	v_add_f32_e32 v33, v33, v28
	ds_read_b128 v[28:31], v18 offset:29696
	s_waitcnt lgkmcnt(1)
	v_mul_f32_e32 v25, v17, v25
	v_fmac_f32_e32 v25, v16, v24
	v_mul_f32_e32 v24, v13, v27
	v_fmac_f32_e32 v24, v12, v26
	s_waitcnt lgkmcnt(0)
	v_mul_f32_e32 v29, v15, v29
	v_add_f32_e32 v24, v25, v24
	v_fmac_f32_e32 v29, v14, v28
	v_mul_f32_e32 v28, v9, v31
	v_add_f32_e32 v33, v33, v24
	ds_read_b128 v[24:27], v18 offset:30720
	v_fmac_f32_e32 v28, v8, v30
	v_add_f32_e32 v28, v29, v28
	v_add_f32_e32 v33, v33, v28
	ds_read_b128 v[28:31], v18 offset:31744
	s_waitcnt lgkmcnt(1)
	v_mul_f32_e32 v25, v5, v25
	v_fmac_f32_e32 v25, v4, v24
	v_mul_f32_e32 v24, v3, v27
	v_fmac_f32_e32 v24, v2, v26
	s_waitcnt lgkmcnt(0)
	v_mul_f32_e32 v29, v11, v29
	v_add_f32_e32 v24, v25, v24
	v_fmac_f32_e32 v29, v10, v28
	v_mul_f32_e32 v28, v7, v31
	v_add_f32_e32 v33, v33, v24
	v_fmac_f32_e32 v28, v6, v30
	ds_read_b128 v[24:27], v18 offset:32768
	v_add_f32_e32 v28, v29, v28
	v_add_f32_e32 v33, v33, v28
	ds_read_b128 v[28:31], v18 offset:33792
	ds_bpermute_b32 v34, v1, v33
	s_waitcnt lgkmcnt(2)
	v_mul_f32_e32 v25, v93, v25
	v_fmac_f32_e32 v25, v92, v24
	v_mul_f32_e32 v24, v89, v27
	v_fmac_f32_e32 v24, v88, v26
	s_waitcnt lgkmcnt(1)
	v_mul_f32_e32 v29, v91, v29
	v_add_f32_e32 v24, v25, v24
	v_fmac_f32_e32 v29, v90, v28
	v_mul_f32_e32 v28, v87, v31
	v_add_f32_e32 v71, 0, v24
	ds_read_b128 v[24:27], v18 offset:34816
	v_fmac_f32_e32 v28, v86, v30
	v_add_f32_e32 v28, v29, v28
	v_add_f32_e32 v71, v71, v28
	ds_read_b128 v[28:31], v18 offset:35840
	s_waitcnt lgkmcnt(1)
	v_mul_f32_e32 v25, v85, v25
	v_fmac_f32_e32 v25, v84, v24
	v_mul_f32_e32 v24, v81, v27
	v_fmac_f32_e32 v24, v80, v26
	s_waitcnt lgkmcnt(0)
	v_mul_f32_e32 v29, v83, v29
	v_add_f32_e32 v24, v25, v24
	v_fmac_f32_e32 v29, v82, v28
	v_mul_f32_e32 v28, v79, v31
	v_add_f32_e32 v71, v71, v24
	ds_read_b128 v[24:27], v18 offset:36864
	v_fmac_f32_e32 v28, v78, v30
	v_add_f32_e32 v28, v29, v28
	v_add_f32_e32 v71, v71, v28
	ds_read_b128 v[28:31], v18 offset:37888
	s_waitcnt lgkmcnt(1)
	v_mul_f32_e32 v17, v17, v25
	v_mul_f32_e32 v13, v13, v27
	v_fmac_f32_e32 v17, v16, v24
	v_fmac_f32_e32 v13, v12, v26
	v_add_f32_e32 v12, v17, v13
	s_waitcnt lgkmcnt(0)
	v_mul_f32_e32 v17, v15, v29
	v_add_f32_e32 v16, v71, v12
	v_fmac_f32_e32 v17, v14, v28
	ds_read_b128 v[12:15], v18 offset:38912
	ds_read_b128 v[24:27], v18 offset:39936
	v_mul_f32_e32 v9, v9, v31
	v_fmac_f32_e32 v9, v8, v30
	v_add_f32_e32 v8, v17, v9
	s_waitcnt lgkmcnt(1)
	v_mul_f32_e32 v5, v5, v13
	v_mul_f32_e32 v3, v3, v15
	v_fmac_f32_e32 v5, v4, v12
	v_fmac_f32_e32 v3, v2, v14
	v_add_f32_e32 v2, v5, v3
	s_waitcnt lgkmcnt(0)
	v_mul_f32_e32 v3, v11, v25
	v_mul_f32_e32 v4, v7, v27
	v_add_f32_e32 v8, v16, v8
	v_fmac_f32_e32 v3, v10, v24
	v_fmac_f32_e32 v4, v6, v26
	v_add_f32_e32 v2, v8, v2
	v_add_f32_e32 v3, v3, v4
	v_add_f32_e32 v2, v2, v3
	ds_bpermute_b32 v3, v1, v2
	v_add_f32_e32 v4, v23, v32
	v_add_f32_e32 v6, v33, v34
	ds_bpermute_b32 v5, v69, v4
	ds_bpermute_b32 v7, v69, v6
	s_waitcnt lgkmcnt(2)
	v_add_f32_e32 v2, v2, v3
	ds_bpermute_b32 v3, v69, v2
	ds_bpermute_b32 v22, v96, v19
	s_waitcnt lgkmcnt(3)
	v_add_f32_e32 v4, v4, v5
	s_waitcnt lgkmcnt(2)
	v_add_f32_e32 v6, v6, v7
	ds_bpermute_b32 v5, v94, v4
	s_waitcnt lgkmcnt(2)
	v_add_f32_e32 v2, v2, v3
	ds_bpermute_b32 v7, v94, v6
	ds_bpermute_b32 v3, v94, v2
	s_waitcnt lgkmcnt(3)
	v_add_f32_e32 v19, v19, v22
	s_waitcnt lgkmcnt(2)
	v_add_f32_e32 v4, v4, v5
	ds_bpermute_b32 v5, v95, v4
	s_waitcnt lgkmcnt(2)
	v_add_f32_e32 v6, v6, v7
	s_waitcnt lgkmcnt(1)
	v_add_f32_e32 v2, v2, v3
	ds_bpermute_b32 v7, v95, v6
	ds_bpermute_b32 v3, v95, v2
	s_waitcnt lgkmcnt(2)
	v_add_f32_e32 v4, v4, v5
	ds_bpermute_b32 v5, v96, v4
	ds_bpermute_b32 v20, v97, v19
	s_waitcnt lgkmcnt(3)
	v_add_f32_e32 v6, v6, v7
	s_waitcnt lgkmcnt(2)
	v_add_f32_e32 v8, v2, v3
	ds_bpermute_b32 v7, v96, v6
	ds_bpermute_b32 v9, v96, v8
	s_waitcnt lgkmcnt(3)
	v_add_f32_e32 v2, v4, v5
	ds_bpermute_b32 v22, v97, v21
	ds_bpermute_b32 v3, v97, v2
	s_waitcnt lgkmcnt(3)
	v_add_f32_e32 v4, v6, v7
	s_waitcnt lgkmcnt(2)
	v_add_f32_e32 v6, v8, v9
	ds_bpermute_b32 v5, v97, v4
	ds_bpermute_b32 v7, v97, v6
	s_and_saveexec_b64 s[8:9], s[40:41]
	s_cbranch_execz .LBB0_74
	global_load_dword v8, v[72:73], off
	s_waitcnt lgkmcnt(1)
	v_add_f32_e32 v4, v4, v5
	v_add_f32_e32 v2, v2, v3
	v_add_f32_e32 v3, v21, v22
	v_add_f32_e32 v5, v19, v20
	s_ashr_i32 s5, s4, 31
	v_cndmask_b32_e64 v3, v5, v3, s[42:43]
	s_lshr_b32 s5, s5, 21
	v_cndmask_b32_e64 v2, v3, v2, s[44:45]
	s_waitcnt lgkmcnt(0)
	v_add_f32_e32 v6, v6, v7
	s_add_i32 s5, s4, s5
	v_cndmask_b32_e64 v2, v2, v4, s[46:47]
	s_ashr_i32 s11, s5, 11
	s_and_b32 s5, s5, 0xfffff800
	v_cndmask_b32_e64 v4, v2, v6, s[48:49]
	s_sub_i32 s10, s4, s5
	v_mad_u64_u32 v[2:3], s[12:13], s11, 5, v[68:69]
	s_mov_b32 s5, 0xbfb8aa3b
	v_readlane_b32 s12, v252, 55
	v_readlane_b32 s13, v252, 56
	s_ashr_i32 s11, s10, 31
	s_waitcnt vmcnt(0)
	v_add_f32_e32 v4, v4, v8
	v_mul_f32_e64 v3, |v4|, s5
	v_exp_f32_e32 v5, v3
	s_mov_b32 s5, 0x800000
	v_ashrrev_i32_e32 v3, 31, v2
	v_lshlrev_b64 v[2:3], 13, v[2:3]
	v_add_f32_e32 v5, 1.0, v5
	v_cmp_gt_f32_e32 vcc, s5, v5
	s_mov_b32 s5, 0x3f317217
	v_lshl_add_u64 v[2:3], s[12:13], 0, v[2:3]
	v_cndmask_b32_e64 v6, 0, 32, vcc
	v_ldexp_f32 v5, v5, v6
	v_log_f32_e32 v5, v5
	v_mov_b32_e32 v6, 0x41b17218
	v_cndmask_b32_e32 v6, 0, v6, vcc
	v_min_f32_e32 v4, 0, v4
	v_mul_f32_e32 v7, 0x3f317217, v5
	v_fma_f32 v7, v5, s5, -v7
	v_fmac_f32_e32 v7, 0x3377d1cf, v5
	s_mov_b32 s5, 0x7f800000
	v_fmac_f32_e32 v7, 0x3f317217, v5
	v_cmp_lt_f32_e64 vcc, |v5|, s5
	v_lshl_add_u64 v[2:3], s[10:11], 2, v[2:3]
	s_nop 0
	v_cndmask_b32_e32 v5, v5, v7, vcc
	v_sub_f32_e32 v5, v5, v6
	v_sub_f32_e32 v4, v4, v5
	global_store_dword v[2:3], v4, off
	s_branch .LBB0_74
